# attention unit prologues: Q loads row-contiguous (full cache lines) + LDS transposition back to the row-per-lane layout
# baseline (speedup 1.0000x reference)
.LBB0_636:
	s_or_b64 exec, exec, s[4:5]
	v_mov_b32_e32 v0, s2
	s_waitcnt lgkmcnt(0)
	s_barrier
	ds_read_b32 v0, v0
	s_mov_b64 s[4:5], -1
	s_waitcnt lgkmcnt(0)
	v_readfirstlane_b32 s3, v0
	s_cmpk_gt_i32 s3, 0x7ff
	s_cbranch_scc1 .LBB0_631
	s_bfe_u32 s34, s3, 0x40006
	s_xor_b32 s39, s34, 15
	s_and_b32 s38, s3, 63
	s_lshl_b32 s35, s39, 2
	s_cmpk_gt_i32 s3, 0x3ff
	s_cbranch_scc0 .LBB0_713
	s_mov_b32 s4, s33
	v_mbcnt_lo_u32_b32 v18, -1, 0
	v_mbcnt_hi_u32_b32 v18, -1, v18
	s_lshl_b32 s10, s39, 8
	v_lshl_or_b32 v19, s4, 6, v18
	s_lshr_b32 s11, s38, 3
	v_readfirstlane_b32 s4, v19
	s_ashr_i32 s5, s4, 1
	s_and_b32 s40, s5, 0xffffffe0
	s_add_i32 s40, s40, s10
	s_and_b32 s14, s3, 7
	s_lshl_b32 s52, s11, 12
	s_ashr_i32 s5, s40, 31
	s_add_u32 s6, s40, s52
	v_and_b32_e32 v20, 31, v18
	s_addc_u32 s5, s5, 0
	v_or_b32_e32 v0, s6, v20
	v_mov_b32_e32 v1, s5
	v_lshlrev_b64 v[134:135], 10, v[0:1]
	v_bfe_u32 v21, v18, 5, 1
	v_lshl_add_u64 v[0:1], s[50:51], 0, v[134:135]
	s_lshl_b32 s96, s14, 7
	v_lshl_add_u64 v[0:1], v[0:1], 0, s[96:97]
	v_lshlrev_b32_e32 v30, 4, v21
	v_mov_b32_e32 v31, v13
	v_lshl_add_u64 v[14:15], v[0:1], 0, v[30:31]
	v_lshrrev_b32_e32 v94, 3, v18
	v_and_b32_e32 v95, 7, v18
	v_readfirstlane_b32 s16, v14
	v_readfirstlane_b32 s17, v15
	v_lshlrev_b32_e32 v96, 10, v94
	v_lshl_add_u32 v96, v95, 4, v96
	v_add_u32_e32 v97, 0x2000, v96
	v_add_u32_e32 v98, 0x4000, v96
	v_add_u32_e32 v99, 0x6000, v96
	s_nop 1
	global_load_dwordx4 v[78:81], v96, s[16:17]
	global_load_dwordx4 v[82:85], v97, s[16:17]
	global_load_dwordx4 v[86:89], v98, s[16:17]
	global_load_dwordx4 v[90:93], v99, s[16:17]
	v_mul_u32_u24_e32 v100, 0x90, v94
	v_lshl_add_u32 v100, v95, 4, v100
	v_mul_u32_u24_e32 v101, 0x90, v20
	v_lshl_add_u32 v101, v21, 4, v101
	s_mul_i32 s16, s33, 0x2200
	s_add_i32 s16, s16, 0xf000
	v_add_u32_e32 v100, s16, v100
	v_add_u32_e32 v101, s16, v101
	s_add_i32 s41, s35, 4
	v_and_b32_e32 v22, 63, v18
	s_cmp_gt_u32 s4, 63
	s_cbranch_scc1 .LBB0_644
	v_cmp_gt_u32_e32 vcc, s41, v22
	s_mov_b64 s[4:5], 0
	s_and_saveexec_b64 s[6:7], vcc
	s_cbranch_execz .LBB0_641
	s_lshl_b32 s4, s38, 4
	v_mov_b32_e32 v12, s4
	v_readlane_b32 s4, v253, 34
	v_readlane_b32 s5, v253, 35
	s_mov_b32 s12, 0xf800000
	s_nop 3
	global_load_dwordx4 v[14:17], v12, s[4:5]
	v_readlane_b32 s16, v253, 44
	v_readlane_b32 s17, v253, 45
	s_lshl_b32 s26, s38, 14
	s_nop 3
	s_add_u32 s16, s16, s26
	s_addc_u32 s17, s17, 0
	s_lshl_b32 s26, s10, 2
	v_mov_b32_e32 v190, s26
	global_load_dword v190, v190, s[16:17]
	v_lshlrev_b32_e32 v191, 8, v22
	global_load_dword v191, v191, s[16:17] offset:252
	s_waitcnt vmcnt(2)
	v_add_f32_e32 v12, v16, v17
	v_cmp_gt_f32_e32 vcc, s12, v12
	v_mul_f32_e32 v16, 0x4f800000, v12
	v_add_f32_e32 v14, v14, v15
	v_cndmask_b32_e32 v12, v12, v16, vcc
	v_sqrt_f32_e32 v16, v12
	v_mul_f32_e32 v15, 0x4f800000, v14
	v_add_u32_e32 v17, -1, v16
	v_fma_f32 v23, -v17, v16, v12
	v_cmp_ge_f32_e64 s[4:5], 0, v23
	v_add_u32_e32 v23, 1, v16
	s_nop 0
	v_cndmask_b32_e64 v17, v16, v17, s[4:5]
	v_fma_f32 v16, -v23, v16, v12
	v_cmp_lt_f32_e64 s[4:5], 0, v16
	s_nop 1
	v_cndmask_b32_e64 v16, v17, v23, s[4:5]
	v_mul_f32_e32 v17, 0x37800000, v16
	v_mov_b32_e32 v23, 0x260
	v_cndmask_b32_e32 v16, v16, v17, vcc
	v_cmp_class_f32_e32 vcc, v12, v23
	s_nop 1
	v_cndmask_b32_e32 v12, v16, v12, vcc
	v_cmp_gt_f32_e32 vcc, s12, v14
	v_readlane_b32 s12, v253, 44
	v_readlane_b32 s13, v253, 45
	v_cndmask_b32_e32 v14, v14, v15, vcc
	v_sqrt_f32_e32 v15, v14
	s_nop 0
	v_add_u32_e32 v16, -1, v15
	v_fma_f32 v17, -v16, v15, v14
	v_cmp_ge_f32_e64 s[4:5], 0, v17
	v_add_u32_e32 v17, 1, v15
	s_nop 0
	v_cndmask_b32_e64 v16, v15, v16, s[4:5]
	v_fma_f32 v15, -v17, v15, v14
	v_cmp_lt_f32_e64 s[4:5], 0, v15
	s_nop 1
	v_cndmask_b32_e64 v15, v16, v17, s[4:5]
	s_lshl_b32 s4, s38, 14
	v_mul_f32_e32 v16, 0x37800000, v15
	s_add_u32 s4, s12, s4
	v_cndmask_b32_e32 v15, v15, v16, vcc
	v_cmp_class_f32_e32 vcc, v14, v23
	s_addc_u32 s5, s13, 0
	s_lshl_b32 s10, s10, 2
	v_cndmask_b32_e32 v14, v15, v14, vcc
	v_mov_b32_e32 v15, s10
	v_mul_f32_e32 v12, v12, v14
	s_mov_b32 s10, 0x3f828f5c
	v_fma_f32 v12, v12, s10, 1.0
	s_waitcnt vmcnt(1)
	v_mov_b32_e32 v15, v190
	v_fmac_f32_e32 v15, 2.0, v12
	s_mov_b32 s4, 0xc2800000
	s_waitcnt vmcnt(0)
	v_sub_f32_e32 v12, v15, v191
	v_cmp_le_f32_e32 vcc, s4, v12
	s_and_b64 s[4:5], vcc, exec

.LBB0_650:
	s_or_b64 exec, exec, s[54:55]
	s_waitcnt vmcnt(0)
	ds_write_b128 v100, v[78:81]
	ds_write_b128 v100, v[82:85] offset:1152
	ds_write_b128 v100, v[86:89] offset:2304
	ds_write_b128 v100, v[90:93] offset:3456
	ds_read_b128 v[0:3], v101
	ds_read_b128 v[4:7], v101 offset:32
	ds_read_b128 v[8:11], v101 offset:64
	ds_read_b128 v[110:113], v101 offset:96
	ds_write_b128 v153, v[114:117] offset:13312
	s_and_saveexec_b64 s[52:53], s[6:7]
	v_xor_b32_e32 v152, 0x80000000, v195
	ds_write_b32 v154, v152 offset:43264
	s_or_b64 exec, exec, s[52:53]
	s_and_b32 s55, s10, 1
	s_lshl_b32 s11, s55, 8
	s_add_i32 s52, s11, 0
	s_mul_i32 s16, s55, 0x3300
	v_add_u32_e32 v26, s52, v30
	s_add_i32 s52, s52, s16
	v_mov_b32_e32 v14, s52
	s_movk_i32 s16, 0x90
	v_mad_u32_u24 v14, v20, s16, v14
	v_add_u32_e32 v163, v14, v30
	s_waitcnt lgkmcnt(0)
	s_barrier
	ds_read_b128 v[190:193], v163
	ds_read_b128 v[46:49], v26 offset:43008
	ds_read_b128 v[50:53], v26 offset:43040
	ds_read_b128 v[54:57], v26 offset:43072
	ds_read_b128 v[58:61], v26 offset:43104
	ds_read_b128 v[198:201], v163 offset:4608
	ds_read_b128 v[62:65], v26 offset:43136
	ds_read_b128 v[66:69], v26 offset:43168
	ds_read_b128 v[70:73], v26 offset:43200
	ds_read_b128 v[74:77], v26 offset:43232
	ds_read_b128 v[194:197], v163 offset:32
	ds_read_b128 v[202:205], v163 offset:4640
	ds_read_b128 v[206:209], v163 offset:64
	ds_read_b128 v[210:213], v163 offset:4672
	ds_read_b128 v[214:217], v163 offset:96
	s_waitcnt lgkmcnt(10)
	v_mfma_f32_32x32x16_bf16 v[46:61], v[190:193], v[0:3], v[46:61]
	ds_read_b128 v[222:225], v163 offset:4704
	s_lshl_b32 s16, s10, 6
	s_or_b32 s17, s16, 63
	v_lshlrev_b32_e32 v156, 2, v21
	s_cmp_le_i32 s17, s40
	v_or_b32_e32 v157, s40, v20
	s_waitcnt lgkmcnt(5)
	v_mfma_f32_32x32x16_bf16 v[46:61], v[194:197], v[4:7], v[46:61]
	s_waitcnt lgkmcnt(6)
	v_mfma_f32_32x32x16_bf16 v[62:77], v[198:201], v[0:3], v[62:77]
	s_waitcnt lgkmcnt(4)
	v_mfma_f32_32x32x16_bf16 v[62:77], v[202:205], v[4:7], v[62:77]
	s_waitcnt lgkmcnt(3)
	v_mfma_f32_32x32x16_bf16 v[46:61], v[206:209], v[8:11], v[46:61]
	s_waitcnt lgkmcnt(2)
	v_mfma_f32_32x32x16_bf16 v[62:77], v[210:213], v[8:11], v[62:77]
	s_waitcnt lgkmcnt(1)
	v_mfma_f32_32x32x16_bf16 v[46:61], v[214:217], v[110:113], v[46:61]
	s_waitcnt lgkmcnt(0)
	v_mfma_f32_32x32x16_bf16 v[62:77], v[222:225], v[110:113], v[62:77]
	s_cbranch_scc1 .LBB0_654
	v_or_b32_e32 v14, s16, v156
	v_or_b32_e32 v15, 32, v14
	v_cmp_le_i32_e32 vcc, v15, v157
	v_or_b32_e32 v15, 33, v14
	s_nop 6
	v_cndmask_b32_e32 v62, v220, v62, vcc
	v_cmp_lt_i32_e32 vcc, v14, v157
	s_nop 1
	v_cndmask_b32_e32 v47, v220, v47, vcc
	v_cmp_le_i32_e32 vcc, v14, v157
	s_nop 1
	v_cndmask_b32_e32 v46, v220, v46, vcc
	v_cmp_le_i32_e32 vcc, v15, v157
	v_or_b32_e32 v15, 2, v14
	s_nop 0
	v_cndmask_b32_e32 v63, v220, v63, vcc
	v_cmp_le_i32_e32 vcc, v15, v157
	v_or_b32_e32 v15, 34, v14
	s_nop 0
	v_cndmask_b32_e32 v48, v220, v48, vcc
	v_cmp_le_i32_e32 vcc, v15, v157
	v_or_b32_e32 v15, 3, v14
	s_nop 0
	v_cndmask_b32_e32 v64, v220, v64, vcc
	v_cmp_le_i32_e32 vcc, v15, v157
	v_or_b32_e32 v15, 35, v14
	s_nop 0
	v_cndmask_b32_e32 v49, v220, v49, vcc
	v_cmp_le_i32_e32 vcc, v15, v157
	v_or_b32_e32 v15, 8, v14
	s_nop 0
	v_cndmask_b32_e32 v65, v220, v65, vcc
	v_cmp_le_i32_e32 vcc, v15, v157
	v_or_b32_e32 v15, 40, v14
	s_nop 0
	v_cndmask_b32_e32 v50, v220, v50, vcc
	v_cmp_le_i32_e32 vcc, v15, v157
	v_or_b32_e32 v15, 9, v14
	s_nop 0
	v_cndmask_b32_e32 v66, v220, v66, vcc
	v_cmp_le_i32_e32 vcc, v15, v157
	v_or_b32_e32 v15, 41, v14
	s_nop 0
	v_cndmask_b32_e32 v51, v220, v51, vcc
	v_cmp_le_i32_e32 vcc, v15, v157
	v_or_b32_e32 v15, 10, v14
	s_nop 0
	v_cndmask_b32_e32 v67, v220, v67, vcc
	v_cmp_le_i32_e32 vcc, v15, v157
	v_or_b32_e32 v15, 42, v14
	s_nop 0
	v_cndmask_b32_e32 v52, v220, v52, vcc
	v_cmp_le_i32_e32 vcc, v15, v157
	v_or_b32_e32 v15, 11, v14
	s_nop 0
	v_cndmask_b32_e32 v68, v220, v68, vcc
	v_cmp_le_i32_e32 vcc, v15, v157
	v_or_b32_e32 v15, 43, v14
	s_nop 0
	v_cndmask_b32_e32 v53, v220, v53, vcc
	v_cmp_le_i32_e32 vcc, v15, v157
	v_or_b32_e32 v15, 16, v14
	s_nop 0
	v_cndmask_b32_e32 v69, v220, v69, vcc
	v_cmp_le_i32_e32 vcc, v15, v157
	v_or_b32_e32 v15, 48, v14
	s_nop 0
	v_cndmask_b32_e32 v54, v220, v54, vcc
	v_cmp_le_i32_e32 vcc, v15, v157
	v_or_b32_e32 v15, 17, v14
	s_nop 0
	v_cndmask_b32_e32 v70, v220, v70, vcc
	v_cmp_le_i32_e32 vcc, v15, v157
	v_or_b32_e32 v15, 49, v14
	s_nop 0
	v_cndmask_b32_e32 v55, v220, v55, vcc
	v_cmp_le_i32_e32 vcc, v15, v157
	v_or_b32_e32 v15, 18, v14
	s_nop 0
	v_cndmask_b32_e32 v71, v220, v71, vcc
	v_cmp_le_i32_e32 vcc, v15, v157
	v_or_b32_e32 v15, 50, v14
	s_nop 0
	v_cndmask_b32_e32 v56, v220, v56, vcc
	v_cmp_le_i32_e32 vcc, v15, v157
	v_or_b32_e32 v15, 19, v14
	s_nop 0
	v_cndmask_b32_e32 v72, v220, v72, vcc
	v_cmp_le_i32_e32 vcc, v15, v157
	v_or_b32_e32 v15, 51, v14
	s_nop 0
	v_cndmask_b32_e32 v57, v220, v57, vcc
	v_cmp_le_i32_e32 vcc, v15, v157
	v_or_b32_e32 v15, 24, v14
	s_nop 0
	v_cndmask_b32_e32 v73, v220, v73, vcc
	v_cmp_le_i32_e32 vcc, v15, v157
	v_or_b32_e32 v15, 56, v14
	s_nop 0
	v_cndmask_b32_e32 v58, v220, v58, vcc
	v_cmp_le_i32_e32 vcc, v15, v157
	v_or_b32_e32 v15, 25, v14
	s_nop 0
	v_cndmask_b32_e32 v74, v220, v74, vcc
	v_cmp_le_i32_e32 vcc, v15, v157
	v_or_b32_e32 v15, 57, v14
	s_nop 0
	v_cndmask_b32_e32 v59, v220, v59, vcc
	v_cmp_le_i32_e32 vcc, v15, v157
	v_or_b32_e32 v15, 26, v14
	s_nop 0
	v_cndmask_b32_e32 v75, v220, v75, vcc
	v_cmp_le_i32_e32 vcc, v15, v157
	v_or_b32_e32 v15, 58, v14
	s_nop 0
	v_cndmask_b32_e32 v60, v220, v60, vcc
	v_cmp_le_i32_e32 vcc, v15, v157
	v_or_b32_e32 v15, 27, v14
	v_or_b32_e32 v14, 59, v14
	v_cndmask_b32_e32 v76, v220, v76, vcc
	v_cmp_le_i32_e32 vcc, v15, v157
	s_nop 1
	v_cndmask_b32_e32 v61, v220, v61, vcc
	v_cmp_le_i32_e32 vcc, v14, v157
	s_nop 1
	v_cndmask_b32_e32 v77, v220, v77, vcc

.LBB0_713:
	s_and_b64 vcc, exec, s[4:5]
	s_cbranch_vccz .LBB0_630
	s_mov_b32 s4, s33
	v_mbcnt_lo_u32_b32 v28, -1, 0
	v_mbcnt_hi_u32_b32 v28, -1, v28
	s_lshl_b32 s5, s39, 8
	v_lshl_or_b32 v30, s4, 6, v28
	s_and_b32 s13, s3, 7
	v_readfirstlane_b32 s4, v30
	s_ashr_i32 s4, s4, 1
	s_and_b32 s39, s4, 0xffffffe0
	s_add_i32 s39, s39, s5
	s_lshl_b32 s4, s38, 9
	s_and_b32 s14, s4, 0x7000
	s_ashr_i32 s4, s39, 31
	v_and_b32_e32 v27, 31, v28
	s_add_u32 s5, s39, s14
	s_addc_u32 s6, s4, 0
	v_or_b32_e32 v146, s5, v27
	v_readlane_b32 s4, v253, 50
	v_readlane_b32 s5, v253, 51
	v_mov_b32_e32 v2, 0x600
	v_bfe_u32 v29, v28, 5, 1
	v_mov_b64_e32 v[0:1], s[4:5]
	v_mad_u64_u32 v[0:1], s[4:5], v146, s92, v[0:1]
	v_mad_i32_i24 v1, s6, v2, v1
	s_mul_i32 s96, s13, 0xc0
	v_lshl_add_u64 v[0:1], v[0:1], 0, s[96:97]
	v_lshlrev_b32_e32 v20, 4, v29
	v_mov_b32_e32 v21, v13
	s_lshl_b32 s4, s14, 10
	v_readlane_b32 s5, v253, 54
	v_lshl_add_u64 v[14:15], v[0:1], 0, v[20:21]
	v_lshrrev_b32_e32 v35, 4, v28
	v_and_b32_e32 v36, 15, v28
	s_mul_i32 s16, s33, 0x2200
	s_add_i32 s16, s16, 0xf000
	v_mul_u32_u24_e32 v37, 0x600, v35
	v_lshl_add_u32 v37, v36, 4, v37
	v_mul_u32_u24_e32 v38, 0xd0, v35
	v_lshl_add_u32 v38, v36, 4, v38
	v_add_u32_e32 v38, s16, v38
	v_mul_u32_u24_e32 v39, 0xd0, v27
	v_lshl_add_u32 v39, v29, 4, v39
	v_add_u32_e32 v39, s16, v39
	v_readfirstlane_b32 s16, v14
	v_readfirstlane_b32 s17, v15
	v_cmp_gt_u32_e32 vcc, 12, v36
	s_nop 4
	s_and_saveexec_b64 s[10:11], vcc
	global_load_dwordx4 v[78:81], v37, s[16:17]
	s_add_u32 s16, s16, 0x1800
	s_addc_u32 s17, s17, 0
	global_load_dwordx4 v[82:85], v37, s[16:17]
	s_add_u32 s16, s16, 0x1800
	s_addc_u32 s17, s17, 0
	global_load_dwordx4 v[86:89], v37, s[16:17]
	s_add_u32 s16, s16, 0x1800
	s_addc_u32 s17, s17, 0
	global_load_dwordx4 v[90:93], v37, s[16:17]
	s_add_u32 s16, s16, 0x1800
	s_addc_u32 s17, s17, 0
	global_load_dwordx4 v[94:97], v37, s[16:17]
	s_add_u32 s16, s16, 0x1800
	s_addc_u32 s17, s17, 0
	global_load_dwordx4 v[98:101], v37, s[16:17]
	s_add_u32 s16, s16, 0x1800
	s_addc_u32 s17, s17, 0
	global_load_dwordx4 v[102:105], v37, s[16:17]
	s_add_u32 s16, s16, 0x1800
	s_addc_u32 s17, s17, 0
	global_load_dwordx4 v[106:109], v37, s[16:17]
	s_or_b64 exec, exec, s[10:11]
	s_add_u32 s4, s5, s4
	v_readlane_b32 s5, v253, 55
	v_and_b32_e32 v32, 7, v28
	s_addc_u32 s5, s5, 0
	s_lshl_b32 s12, s13, 7
	v_ashrrev_i32_e32 v31, 3, v30
	s_add_u32 s4, s4, s12
	v_lshlrev_b32_e32 v12, 3, v32
	s_addc_u32 s5, s5, 0
	v_lshl_or_b32 v148, v31, 9, v12
	v_mov_b32_e32 v149, v13
	v_lshl_add_u64 v[24:25], v[148:149], 1, s[4:5]
	s_barrier
	global_load_dwordx4 v[16:19], v[24:25], off
	s_lshl_b32 s96, s14, 6
	v_readlane_b32 s4, v253, 40
	v_ashrrev_i32_e32 v33, 2, v30
	v_and_b32_e32 v34, 3, v28
	v_mov_b32_e32 v14, v13
	v_mov_b32_e32 v15, v13
	v_mov_b32_e32 v147, s6
	v_readlane_b32 s5, v253, 41
	s_add_u32 s4, s4, s96
	v_lshlrev_b32_e32 v21, 5, v33
	v_lshlrev_b32_e32 v26, 3, v34
	s_movk_i32 s6, 0x100
	v_mov_b32_e32 v12, v13
	v_mov_b64_e32 v[124:125], v[14:15]
	s_addc_u32 s5, s5, 0
	v_or_b32_e32 v22, v21, v26
	v_cmp_gt_i32_e64 s[6:7], s6, v30
	v_mov_b64_e32 v[122:123], v[12:13]
	s_and_saveexec_b64 s[10:11], s[6:7]
	s_cbranch_execz .LBB0_716
	v_mov_b32_e32 v23, v13
	v_lshl_add_u64 v[14:15], v[22:23], 1, s[4:5]
	global_load_dwordx4 v[122:125], v[14:15], off

.Lmpro_nokr1:
	s_or_b64 exec, exec, s[10:11]
	v_lshlrev_b32_e32 v15, 4, v34
	v_add_u32_e32 v158, 0, v31
	s_movk_i32 s16, 0xd0
	s_waitcnt vmcnt(2)
	ds_write_b128 v158, v[16:19]
	v_add3_u32 v16, v14, v15, 0
	s_and_saveexec_b64 s[10:11], s[6:7]
	ds_write_b128 v16, v[122:125] offset:128
	s_or_b64 exec, exec, s[10:11]
	v_lshlrev_b32_e32 v17, 12, v23
	v_lshlrev_b32_e32 v18, 6, v30
	v_or3_b32 v17, v15, v17, v18
	v_add_co_u32_e32 v18, vcc, 0x10000, v24
	v_add_u32_e32 v159, 0, v17
	s_nop 0
	v_addc_co_u32_e32 v19, vcc, 0, v25, vcc
	s_waitcnt vmcnt(1)
	ds_write_b128 v159, v[130:133] offset:26624
	s_waitcnt vmcnt(0)
	v_cmp_gt_u32_e32 vcc, 12, v36
	s_and_saveexec_b64 s[4:5], vcc
	ds_write_b128 v38, v[78:81]
	ds_write_b128 v38, v[82:85] offset:832
	ds_write_b128 v38, v[86:89] offset:1664
	ds_write_b128 v38, v[90:93] offset:2496
	ds_write_b128 v38, v[94:97] offset:3328
	ds_write_b128 v38, v[98:101] offset:4160
	ds_write_b128 v38, v[102:105] offset:4992
	ds_write_b128 v38, v[106:109] offset:5824
	s_or_b64 exec, exec, s[4:5]
	ds_read_b128 v[0:3], v39
	ds_read_b128 v[4:7], v39 offset:32
	ds_read_b128 v[8:11], v39 offset:64
	ds_read_b128 v[110:113], v39 offset:96
	ds_read_b128 v[114:117], v39 offset:128
	ds_read_b128 v[118:121], v39 offset:160
	ds_write_b128 v158, v[126:129] offset:13312
	s_and_saveexec_b64 s[4:5], s[6:7]
	ds_write_b128 v16, v[194:197] offset:13440
	s_or_b64 exec, exec, s[4:5]
	v_lshlrev_b32_e32 v17, 3, v28
	v_lshlrev_b32_e32 v16, 1, v28
	v_and_b32_e32 v17, 24, v17
	v_and_or_b32 v16, v16, 32, v17
	v_lshlrev_b32_e32 v160, 2, v29
	v_lshrrev_b32_e32 v17, 2, v28
	v_and_or_b32 v17, v17, 3, v160
	v_lshl_or_b32 v161, v17, 6, v16
	v_mad_u32_u24 v16, v27, s16, 0
	v_add_u32_e32 v162, v16, v20
	s_waitcnt lgkmcnt(0)
	s_barrier
	ds_read_b128 v[190:193], v162 offset:6656
	ds_read_b128 v[194:197], v162
	ds_read_b128 v[198:201], v162 offset:32
	ds_read_b128 v[202:205], v162 offset:6688
	ds_read_b128 v[206:209], v162 offset:64
	ds_read_b128 v[210:213], v162 offset:6720
	ds_read_b128 v[214:217], v162 offset:96
	ds_read_b128 v[222:225], v162 offset:6752
	ds_read_b128 v[226:229], v162 offset:128
	ds_read_b128 v[230:233], v162 offset:6784
	ds_read_b128 v[16:19], v162 offset:160
	ds_read_b128 v[22:25], v162 offset:6816
	s_waitcnt lgkmcnt(11)
	v_mfma_f32_32x32x16_bf16 v[62:77], v[190:193], v[0:3], 0
	s_add_i32 s35, s35, 4
	s_mov_b32 s52, 0
	s_cmp_eq_u32 s34, 15
	v_add_u32_e32 v163, v14, v15
	v_add_u32_e32 v150, v21, v26
	s_waitcnt lgkmcnt(10)
	v_mfma_f32_32x32x16_bf16 v[46:61], v[194:197], v[0:3], 0
	s_waitcnt lgkmcnt(9)
	v_mfma_f32_32x32x16_bf16 v[46:61], v[198:201], v[4:7], v[46:61]
	s_waitcnt lgkmcnt(8)
	v_mfma_f32_32x32x16_bf16 v[62:77], v[202:205], v[4:7], v[62:77]
	s_waitcnt lgkmcnt(7)
	v_mfma_f32_32x32x16_bf16 v[46:61], v[206:209], v[8:11], v[46:61]
	s_waitcnt lgkmcnt(6)
	v_mfma_f32_32x32x16_bf16 v[62:77], v[210:213], v[8:11], v[62:77]
	s_waitcnt lgkmcnt(5)
	v_mfma_f32_32x32x16_bf16 v[46:61], v[214:217], v[110:113], v[46:61]
	s_waitcnt lgkmcnt(4)
	v_mfma_f32_32x32x16_bf16 v[62:77], v[222:225], v[110:113], v[62:77]
	s_waitcnt lgkmcnt(3)
	v_mfma_f32_32x32x16_bf16 v[46:61], v[226:229], v[114:117], v[46:61]
	s_waitcnt lgkmcnt(2)
	v_mfma_f32_32x32x16_bf16 v[62:77], v[230:233], v[114:117], v[62:77]
	s_waitcnt lgkmcnt(0)
	s_barrier
	v_mfma_f32_32x32x16_bf16 v[46:61], v[16:19], v[118:121], v[46:61]
	v_mfma_f32_32x32x16_bf16 v[62:77], v[22:25], v[118:121], v[62:77]
	v_mov_b32_e32 v14, 0
	v_mov_b32_e32 v15, 0
	v_mov_b32_e32 v16, 0
	v_mov_b32_e32 v17, 0
	v_mov_b32_e32 v18, 0
	v_mov_b32_e32 v19, 0
	v_mov_b32_e32 v20, 0
	v_mov_b32_e32 v21, 0
	v_mov_b32_e32 v22, 0
	v_mov_b32_e32 v23, 0
	v_mov_b32_e32 v24, 0
	v_mov_b32_e32 v25, 0
	v_mov_b32_e32 v26, 0
	v_mov_b32_e32 v27, 0
	v_mov_b32_e32 v28, 0
	v_mov_b32_e32 v29, 0
	v_mov_b32_e32 v30, 0
	v_mov_b32_e32 v31, 0
	v_mov_b32_e32 v32, 0
	v_mov_b32_e32 v33, 0
	v_mov_b32_e32 v34, 0
	v_mov_b32_e32 v35, 0
	v_mov_b32_e32 v36, 0
	v_mov_b32_e32 v37, 0
	v_mov_b32_e32 v38, 0
	v_mov_b32_e32 v39, 0
	v_mov_b32_e32 v40, 0
	v_mov_b32_e32 v41, 0
	v_mov_b32_e32 v42, 0
	v_mov_b32_e32 v43, 0
	v_mov_b32_e32 v44, 0
	v_mov_b32_e32 v45, 0
	v_mov_b32_e32 v165, 0
	s_and_b32 s4, s3, 56
	s_lshl_b32 s4, s4, 19
	s_or_b32 s4, s4, s12
	s_add_u32 s54, s22, s4
	s_addc_u32 s55, s23, 0
	s_add_u32 s54, s54, 0x15a20000
	s_addc_u32 s55, s55, 0
	s_add_u32 s56, s22, s96
	s_addc_u32 s57, s23, 0
	s_add_u32 s56, s56, 0x12802000
	s_addc_u32 s57, s57, 0
	v_lshlrev_b32_e32 v226, 1, v148
	v_lshlrev_b32_e32 v227, 1, v12
	v_add_u32_e32 v227, 0x1ff0000, v227
	v_lshlrev_b32_e32 v228, 1, v150
	global_load_dwordx4 v[126:129], v226, s[54:55]
	s_and_saveexec_b64 s[4:5], s[6:7]
	s_cbranch_execz .Lm3_nokrp
	global_load_dwordx4 v[122:125], v228, s[56:57]
